# plus batched barrier-census loads and unrolled x->bf16 loop (8 loads in flight)
# speedup vs baseline: 1.0017x; 1.0017x over previous
; DI unsigned pk2(float lo, float hi) { f32x2 v = {lo, hi}; return __builtin_bit_cast(unsigned, __builtin_convertvector(v, bf2_t)); }
; DI void convert_range(const Args& a, LAS unsigned char* lds, int lo_, int hi_, int blk, int nblk, int wave, int lane, bool with_x) {
;     ...
;     if (with_x) {
;         const f32x4* xs = (const f32x4*)a.in[0]; u32x2* xb = (u32x2*)(ws + WS_XB);
;         const size_t n4 = (size_t)M * D / 4, stride = (size_t)nblk * NTHREADS;
;         for (size_t i = (size_t)blk * NTHREADS + wave * 64 + lane; i < n4; i += stride) { const f32x4 v = xs[i]; u32x2 o; o.x = pk2(v[0], v[1]); o.y = pk2(v[2], v[3]); xb[i] = o; }
;     }
.LBB0_555:
	s_andn2_b32 s3, s3, 63
	s_ashr_i32 s1, s3, 31
	v_readlane_b32 s4, v253, 34
	v_readlane_b32 s5, v253, 35
	s_add_u32 s0, s4, s3
	s_addc_u32 s1, s5, s1
	s_waitcnt vmcnt(0)
	v_mov_b64_e32 v[0:1], 0x3fffff
	v_cmp_gt_u64_e32 vcc, s[0:1], v[0:1]
	s_cbranch_vccnz .LBB0_559
	v_mov_b32_e32 v135, v97
	v_or_b32_e32 v0, s0, v134
	v_mov_b32_e32 v1, s1
	v_lshl_add_u64 v[4:5], s[0:1], 0, v[134:135]
	v_readlane_b32 s0, v253, 11
	v_readlane_b32 s1, v253, 12
	s_waitcnt lgkmcnt(0)
	v_lshl_add_u64 v[2:3], v[4:5], 4, s[56:57]
	v_lshl_add_u64 v[4:5], v[4:5], 3, s[0:1]
	s_mov_b64 s[0:1], 0
	s_cmp_lg_u32 s98, 0x20000
	s_cbranch_scc1 .LBB0_557
	s_cmp_lg_u32 s99, 0
	s_cbranch_scc1 .LBB0_557
	s_mov_b32 s4, 4
.Lxcv_batch:
	global_load_dwordx4 v[6:9], v[2:3], off
	v_lshl_add_u64 v[2:3], v[2:3], 0, s[54:55]
	global_load_dwordx4 v[10:13], v[2:3], off
	v_lshl_add_u64 v[2:3], v[2:3], 0, s[54:55]
	global_load_dwordx4 v[14:17], v[2:3], off
	v_lshl_add_u64 v[2:3], v[2:3], 0, s[54:55]
	global_load_dwordx4 v[18:21], v[2:3], off
	v_lshl_add_u64 v[2:3], v[2:3], 0, s[54:55]
	global_load_dwordx4 v[22:25], v[2:3], off
	v_lshl_add_u64 v[2:3], v[2:3], 0, s[54:55]
	global_load_dwordx4 v[26:29], v[2:3], off
	v_lshl_add_u64 v[2:3], v[2:3], 0, s[54:55]
	global_load_dwordx4 v[30:33], v[2:3], off
	v_lshl_add_u64 v[2:3], v[2:3], 0, s[54:55]
	global_load_dwordx4 v[34:37], v[2:3], off
	v_lshl_add_u64 v[2:3], v[2:3], 0, s[54:55]
	s_waitcnt vmcnt(7)
	v_cvt_pk_bf16_f32 v6, v6, v7
	v_cvt_pk_bf16_f32 v7, v8, v9
	global_store_dwordx2 v[4:5], v[6:7], off
	v_lshl_add_u64 v[4:5], v[4:5], 0, s[34:35]
	s_waitcnt vmcnt(7)
	v_cvt_pk_bf16_f32 v10, v10, v11
	v_cvt_pk_bf16_f32 v11, v12, v13
	global_store_dwordx2 v[4:5], v[10:11], off
	v_lshl_add_u64 v[4:5], v[4:5], 0, s[34:35]
	s_waitcnt vmcnt(7)
	v_cvt_pk_bf16_f32 v14, v14, v15
	v_cvt_pk_bf16_f32 v15, v16, v17
	global_store_dwordx2 v[4:5], v[14:15], off
	v_lshl_add_u64 v[4:5], v[4:5], 0, s[34:35]
	s_waitcnt vmcnt(7)
	v_cvt_pk_bf16_f32 v18, v18, v19
	v_cvt_pk_bf16_f32 v19, v20, v21
	global_store_dwordx2 v[4:5], v[18:19], off
	v_lshl_add_u64 v[4:5], v[4:5], 0, s[34:35]
	s_waitcnt vmcnt(7)
	v_cvt_pk_bf16_f32 v22, v22, v23
	v_cvt_pk_bf16_f32 v23, v24, v25
	global_store_dwordx2 v[4:5], v[22:23], off
	v_lshl_add_u64 v[4:5], v[4:5], 0, s[34:35]
	s_waitcnt vmcnt(7)
	v_cvt_pk_bf16_f32 v26, v26, v27
	v_cvt_pk_bf16_f32 v27, v28, v29
	global_store_dwordx2 v[4:5], v[26:27], off
	v_lshl_add_u64 v[4:5], v[4:5], 0, s[34:35]
	s_waitcnt vmcnt(7)
	v_cvt_pk_bf16_f32 v30, v30, v31
	v_cvt_pk_bf16_f32 v31, v32, v33
	global_store_dwordx2 v[4:5], v[30:31], off
	v_lshl_add_u64 v[4:5], v[4:5], 0, s[34:35]
	s_waitcnt vmcnt(7)
	v_cvt_pk_bf16_f32 v34, v34, v35
	v_cvt_pk_bf16_f32 v35, v36, v37
	global_store_dwordx2 v[4:5], v[34:35], off
	v_lshl_add_u64 v[4:5], v[4:5], 0, s[34:35]
	s_sub_u32 s4, s4, 1
	s_cmp_lg_u32 s4, 0
	s_cbranch_scc1 .Lxcv_batch
	s_branch .LBB0_559
